# mLSTM: the chunk's eight v-row loads use a pointer walking by the row pitch instead of eight rebuilt 64-bit addresses (40 -> 22 instructions)
# baseline (speedup 1.0000x reference)
; #define LAS __attribute__((address_space(3)))
; __device__ __forceinline__ unsigned pk2(float lo, float hi) { const f32x2 v = {lo, hi}; const bf16x2n b = __builtin_convertvector(v, bf16x2n); return __builtin_bit_cast(unsigned, b); }
; __device__ __forceinline__ float siluf_(float x) { return x * rcp_(1.0f + __expf(-x)); }
; __device__ __forceinline__ void ml_block(KP p, int e, int b, int hd, int half, LAS unsigned char* lds, const bf16_t* P, bf16_t* YB) {
;     ...
;             const float blast = Bc[63];
;             unsigned vr[8];
; #pragma unroll
;             for (int i = 0; i < 8; ++i) vr[i] = *(const unsigned*)(P + (rbase + tb + tg * 8 + i) * NPROJ + 2048 + hd * 128 + 2 * d2);
;             f32x2 wq[4], wk[4];
; #pragma unroll
;             for (int tp = 0; tp < 4; ++tp) { wq[tp] = *(const LAS f32x2*)(CW + tp * 256 + 2 * d2); wk[tp] = *(const LAS f32x2*)(CW + tp * 256 + 128 + 2 * d2); }
;             const f32x2 bq = *(const LAS f32x2*)(CW + 1024 + 2 * d2), bk = *(const LAS f32x2*)(CW + 1024 + 128 + 2 * d2);
;             float kw0[8], kw1[8];
; #pragma unroll
;             for (int i = 0; i < 8; ++i) {
;                 const int j = tg * 8 + i;
;                 f32x2 aq = bq, ak = bk;
; #pragma unroll
;                 for (int tp = 0; tp < 4; ++tp) {
;                     const f32x2 xq = {__uint_as_float(qr[i + tp] << 16), __uint_as_float(qr[i + tp] & 0xFFFF0000u)}, xk = {__uint_as_float(kr[i + tp] << 16), __uint_as_float(kr[i + tp] & 0xFFFF0000u)};
;                     aq = wq[tp] * xq + aq; ak = wk[tp] * xk + ak;
;                 }
;                 const float q0 = siluf_(aq.x) * qscale, q1 = siluf_(aq.y) * qscale, k0 = siluf_(ak.x), k1 = siluf_(ak.y);
;                 *(LAS unsigned*)(Qs + j * 136 + 2 * d2) = pk2(q0, q1);
;                 *(LAS unsigned*)(Ks + j * 136 + 2 * d2) = pk2(k0, k1);
;                 const float wkj = __expf(blast - Bc[j] + Ip[j]);
;                 kw0[i] = wkj * k0; kw1[i] = wkj * k1;
;             }
.LBB0_327:
	s_and_b32 s7, s53, 1
	s_add_i32 s33, 0, 0x1de00
	s_cmpk_lg_i32 s52, 0xfc0
	s_cselect_b64 s[42:43], -1, 0
	s_cmp_eq_u32 s7, 0
	s_cselect_b64 s[44:45], -1, 0
	s_and_b64 s[46:47], s[44:45], exec
	s_cselect_b32 s7, s60, s61
	v_mov_b32_e32 v42, s7
	ds_read_b32 v184, v42
	v_lshl_add_u64 v[42:43], s[50:51], 0, v[102:103]
	v_add_co_u32_e32 v44, vcc, s64, v42
	s_cselect_b32 s56, s33, s4
	s_mov_b64 s[78:79], 0x1a00
	v_addc_co_u32_e32 v45, vcc, 0, v43, vcc
	global_load_dword v178, v[44:45], off
	v_lshl_add_u64 v[42:43], v[44:45], 0, s[78:79]
	global_load_dword v179, v[42:43], off
	s_waitcnt vmcnt(4)
	v_lshlrev_b32_e32 v104, 16, v116
	v_lshl_add_u64 v[44:45], v[42:43], 0, s[78:79]
	global_load_dword v180, v[44:45], off
	v_lshl_add_u64 v[42:43], v[44:45], 0, s[78:79]
	global_load_dword v181, v[42:43], off
	v_lshl_add_u64 v[44:45], v[42:43], 0, s[78:79]
	global_load_dword v182, v[44:45], off
	v_and_b32_e32 v105, 0xffff0000, v116
	v_lshl_add_u64 v[42:43], v[44:45], 0, s[78:79]
	global_load_dword v183, v[42:43], off
	v_lshl_add_u64 v[44:45], v[42:43], 0, s[78:79]
	global_load_dword v185, v[44:45], off
	v_lshl_add_u64 v[42:43], v[44:45], 0, s[78:79]
	global_load_dword v186, v[42:43], off
	ds_read_b64 v[58:59], v151
	ds_read_b64 v[60:61], v152
	ds_read_b64 v[66:67], v153
	ds_read_b64 v[68:69], v154
	ds_read_b64 v[70:71], v155
	ds_read_b64 v[72:73], v156
	ds_read_b64 v[62:63], v157
	ds_read_b64 v[64:65], v158
	ds_read_b64 v[74:75], v138
	ds_read_b64 v[76:77], v139
	v_lshlrev_b32_e32 v42, 16, v113
	v_and_b32_e32 v43, 0xffff0000, v113
	v_lshlrev_b32_e32 v108, 16, v118
	s_waitcnt lgkmcnt(1)
	v_pk_fma_f32 v[42:43], v[58:59], v[42:43], v[74:75]
	v_and_b32_e32 v109, 0xffff0000, v118
	v_pk_fma_f32 v[42:43], v[66:67], v[104:105], v[42:43]
	v_lshlrev_b32_e32 v78, 16, v120
	v_pk_fma_f32 v[42:43], v[70:71], v[108:109], v[42:43]
	v_and_b32_e32 v79, 0xffff0000, v120
	v_pk_fma_f32 v[42:43], v[62:63], v[78:79], v[42:43]
	s_waitcnt vmcnt(9)
	v_lshlrev_b32_e32 v44, 16, v115
	v_mul_f32_e32 v46, 0xbfb8aa3b, v42
	v_mul_f32_e32 v47, 0xbfb8aa3b, v43
	v_exp_f32_e32 v46, v46
	v_exp_f32_e32 v47, v47
	v_and_b32_e32 v45, 0xffff0000, v115
	s_waitcnt lgkmcnt(0)
	v_pk_fma_f32 v[44:45], v[60:61], v[44:45], v[76:77]
	v_add_f32_e32 v46, 1.0, v46
	v_add_f32_e32 v47, 1.0, v47
	v_lshlrev_b32_e32 v106, 16, v117
	v_and_b32_e32 v107, 0xffff0000, v117
	v_rcp_f32_e32 v46, v46
	v_rcp_f32_e32 v47, v47
	v_pk_fma_f32 v[44:45], v[68:69], v[106:107], v[44:45]
	v_lshlrev_b32_e32 v110, 16, v119
	v_and_b32_e32 v111, 0xffff0000, v119
	v_pk_fma_f32 v[44:45], v[72:73], v[110:111], v[44:45]
	v_lshlrev_b32_e32 v80, 16, v121
	v_and_b32_e32 v81, 0xffff0000, v121
	v_pk_fma_f32 v[44:45], v[64:65], v[80:81], v[44:45]
	v_pk_mul_f32 v[42:43], v[42:43], v[46:47]
	v_mul_f32_e32 v46, 0xbfb8aa3b, v44
	v_mul_f32_e32 v47, 0xbfb8aa3b, v45
	v_exp_f32_e32 v46, v46
	v_exp_f32_e32 v47, v47
	v_pk_mul_f32 v[42:43], v[42:43], s[80:81] op_sel_hi:[1,0]
	s_cselect_b32 s69, s62, s63
	v_add_f32_e32 v46, 1.0, v46
	v_add_f32_e32 v47, 1.0, v47
	v_rcp_f32_e32 v46, v46
	v_rcp_f32_e32 v47, v47
	v_cvt_pk_bf16_f32 v42, v42, v43
	v_pk_fma_f32 v[104:105], v[58:59], v[104:105], v[74:75]
	v_pk_fma_f32 v[106:107], v[60:61], v[106:107], v[76:77]
	v_pk_mul_f32 v[188:189], v[44:45], v[46:47]
	v_lshlrev_b32_e32 v46, 2, v84
	v_cvt_pk_bf16_f32 v43, v188, v189
	ds_write2st64_b32 v92, v42, v43 offset1:68
	v_add_u32_e32 v42, s56, v46
	ds_read_b128 v[50:53], v42
	ds_read_b128 v[42:45], v42 offset:16
	v_add_u32_e32 v46, s69, v46
	ds_read_b128 v[54:57], v46
	ds_read_b128 v[46:49], v46 offset:16
	v_pk_fma_f32 v[104:105], v[66:67], v[108:109], v[104:105]
	s_waitcnt lgkmcnt(3)
	v_sub_f32_e32 v50, v184, v50
	v_pk_fma_f32 v[190:191], v[70:71], v[78:79], v[104:105]
	v_lshlrev_b32_e32 v104, 16, v122
	v_and_b32_e32 v105, 0xffff0000, v122
	v_pk_fma_f32 v[190:191], v[62:63], v[104:105], v[190:191]
	s_waitcnt lgkmcnt(1)
	v_add_f32_e32 v50, v50, v54
	v_mul_f32_e32 v54, 0xbfb8aa3b, v190
	v_exp_f32_e32 v54, v54
	v_pk_fma_f32 v[106:107], v[68:69], v[110:111], v[106:107]
	v_pk_fma_f32 v[108:109], v[58:59], v[108:109], v[74:75]
	v_pk_fma_f32 v[192:193], v[72:73], v[80:81], v[106:107]
	v_add_f32_e32 v54, 1.0, v54
	v_rcp_f32_e32 v210, v54
	v_mul_f32_e32 v54, 0xbfb8aa3b, v191
	v_exp_f32_e32 v54, v54
	v_lshlrev_b32_e32 v106, 16, v123
	v_and_b32_e32 v107, 0xffff0000, v123
	v_pk_fma_f32 v[192:193], v[64:65], v[106:107], v[192:193]
	v_add_f32_e32 v54, 1.0, v54
	v_rcp_f32_e32 v211, v54
	v_mul_f32_e32 v54, 0xbfb8aa3b, v192
	v_exp_f32_e32 v54, v54
	v_sub_f32_e32 v51, v184, v51
	v_pk_mul_f32 v[190:191], v[190:191], v[210:211]
	v_pk_fma_f32 v[108:109], v[66:67], v[78:79], v[108:109]
	v_add_f32_e32 v54, 1.0, v54
	v_rcp_f32_e32 v210, v54
	v_mul_f32_e32 v54, 0xbfb8aa3b, v193
	v_exp_f32_e32 v54, v54
	v_pk_mul_f32 v[190:191], v[190:191], s[80:81] op_sel_hi:[1,0]
	v_add_f32_e32 v51, v51, v55
	v_mul_f32_e32 v50, 0x3fb8aa3b, v50
	v_add_f32_e32 v54, 1.0, v54
	v_rcp_f32_e32 v211, v54
	v_cvt_pk_bf16_f32 v54, v190, v191
	v_mul_f32_e32 v51, 0x3fb8aa3b, v51
	v_exp_f32_e32 v50, v50
	v_pk_mul_f32 v[192:193], v[192:193], v[210:211]
	v_exp_f32_e32 v51, v51
	v_cvt_pk_bf16_f32 v187, v192, v193
	ds_write2st64_b32 v94, v54, v187 offset1:68
	v_mov_b32_e32 v54, v188
	v_mov_b32_e32 v55, v192
	v_mov_b32_e32 v192, v189
	v_pk_fma_f32 v[188:189], v[70:71], v[104:105], v[108:109]
	v_lshlrev_b32_e32 v108, 16, v125
	v_and_b32_e32 v109, 0xffff0000, v125
	v_pk_fma_f32 v[188:189], v[62:63], v[108:109], v[188:189]
	v_pk_mul_f32 v[54:55], v[50:51], v[54:55]
	v_mul_f32_e32 v187, 0xbfb8aa3b, v188
	v_exp_f32_e32 v187, v187
	v_pk_mul_f32 v[50:51], v[50:51], v[192:193]
	v_pk_fma_f32 v[110:111], v[60:61], v[110:111], v[76:77]
; #define LAS __attribute__((address_space(3)))
; __device__ __forceinline__ unsigned pk2(float lo, float hi) { const f32x2 v = {lo, hi}; const bf16x2n b = __builtin_convertvector(v, bf16x2n); return __builtin_bit_cast(unsigned, b); }
; __device__ __forceinline__ float siluf_(float x) { return x * rcp_(1.0f + __expf(-x)); }
; __device__ __forceinline__ void ml_block(KP p, int e, int b, int hd, int half, LAS unsigned char* lds, const bf16_t* P, bf16_t* YB) {
;     ...
; #pragma unroll
;             for (int i = 0; i < 8; ++i) {
;                 const int j = tg * 8 + i;
;                 f32x2 aq = bq, ak = bk;
; #pragma unroll
;                 for (int tp = 0; tp < 4; ++tp) {
;                     const f32x2 xq = {__uint_as_float(qr[i + tp] << 16), __uint_as_float(qr[i + tp] & 0xFFFF0000u)}, xk = {__uint_as_float(kr[i + tp] << 16), __uint_as_float(kr[i + tp] & 0xFFFF0000u)};
;                     aq = wq[tp] * xq + aq; ak = wk[tp] * xk + ak;
;                 }
;                 const float q0 = siluf_(aq.x) * qscale, q1 = siluf_(aq.y) * qscale, k0 = siluf_(ak.x), k1 = siluf_(ak.y);
;                 *(LAS unsigned*)(Qs + j * 136 + 2 * d2) = pk2(q0, q1);
;                 *(LAS unsigned*)(Ks + j * 136 + 2 * d2) = pk2(k0, k1);
;                 const float wkj = __expf(blast - Bc[j] + Ip[j]);
;                 kw0[i] = wkj * k0; kw1[i] = wkj * k1;
;             }
	v_pk_fma_f32 v[78:79], v[58:59], v[78:79], v[74:75]
	v_add_f32_e32 v187, 1.0, v187
	v_rcp_f32_e32 v192, v187
	v_mul_f32_e32 v187, 0xbfb8aa3b, v189
	v_exp_f32_e32 v187, v187
	v_pk_fma_f32 v[110:111], v[68:69], v[80:81], v[110:111]
	v_pk_fma_f32 v[78:79], v[66:67], v[104:105], v[78:79]
	v_pk_fma_f32 v[190:191], v[72:73], v[106:107], v[110:111]
	v_lshlrev_b32_e32 v110, 16, v126
	v_and_b32_e32 v111, 0xffff0000, v126
	v_pk_fma_f32 v[190:191], v[64:65], v[110:111], v[190:191]
	v_add_f32_e32 v187, 1.0, v187
	v_rcp_f32_e32 v193, v187
	v_mul_f32_e32 v187, 0xbfb8aa3b, v190
	v_exp_f32_e32 v187, v187
	v_sub_f32_e32 v52, v184, v52
	v_pk_mul_f32 v[188:189], v[188:189], v[192:193]
	v_add_f32_e32 v52, v52, v56
	v_add_f32_e32 v187, 1.0, v187
	v_rcp_f32_e32 v192, v187
	v_mul_f32_e32 v187, 0xbfb8aa3b, v191
	v_exp_f32_e32 v187, v187
	v_pk_mul_f32 v[188:189], v[188:189], s[80:81] op_sel_hi:[1,0]
	v_pk_fma_f32 v[80:81], v[60:61], v[80:81], v[76:77]
	v_pk_fma_f32 v[104:105], v[58:59], v[104:105], v[74:75]
	v_add_f32_e32 v187, 1.0, v187
	v_rcp_f32_e32 v193, v187
	v_cvt_pk_bf16_f32 v187, v188, v189
	v_pk_fma_f32 v[80:81], v[68:69], v[106:107], v[80:81]
	v_pk_fma_f32 v[104:105], v[66:67], v[108:109], v[104:105]
	v_pk_mul_f32 v[190:191], v[190:191], v[192:193]
	v_pk_fma_f32 v[192:193], v[72:73], v[110:111], v[80:81]
	v_cvt_pk_bf16_f32 v188, v190, v191
	ds_write2st64_b32 v93, v187, v188 offset1:68
	v_pk_fma_f32 v[188:189], v[70:71], v[108:109], v[78:79]
	v_lshlrev_b32_e32 v78, 16, v127
	v_and_b32_e32 v79, 0xffff0000, v127
	v_pk_fma_f32 v[188:189], v[62:63], v[78:79], v[188:189]
	v_lshlrev_b32_e32 v80, 16, v128
	v_mul_f32_e32 v56, 0xbfb8aa3b, v188
	v_exp_f32_e32 v56, v56
	v_and_b32_e32 v81, 0xffff0000, v128
	v_pk_fma_f32 v[192:193], v[64:65], v[80:81], v[192:193]
	v_sub_f32_e32 v53, v184, v53
	v_add_f32_e32 v56, 1.0, v56
	v_rcp_f32_e32 v210, v56
	v_mul_f32_e32 v56, 0xbfb8aa3b, v189
	v_exp_f32_e32 v56, v56
	v_add_f32_e32 v53, v53, v57
	v_mul_f32_e32 v52, 0x3fb8aa3b, v52
	v_mul_f32_e32 v53, 0x3fb8aa3b, v53
	v_add_f32_e32 v56, 1.0, v56
	v_rcp_f32_e32 v211, v56
	v_mul_f32_e32 v56, 0xbfb8aa3b, v192
	v_exp_f32_e32 v56, v56
	v_exp_f32_e32 v52, v52
	v_pk_mul_f32 v[188:189], v[188:189], v[210:211]
	v_exp_f32_e32 v53, v53
	v_add_f32_e32 v56, 1.0, v56
	v_rcp_f32_e32 v210, v56
	v_mul_f32_e32 v56, 0xbfb8aa3b, v193
	v_exp_f32_e32 v56, v56
	v_pk_mul_f32 v[188:189], v[188:189], s[80:81] op_sel_hi:[1,0]
	v_pk_fma_f32 v[106:107], v[60:61], v[106:107], v[76:77]
	v_pk_fma_f32 v[108:109], v[58:59], v[108:109], v[74:75]
	v_add_f32_e32 v56, 1.0, v56
	v_rcp_f32_e32 v211, v56
	v_cvt_pk_bf16_f32 v56, v188, v189
	v_pk_fma_f32 v[188:189], v[70:71], v[78:79], v[104:105]
	v_lshlrev_b32_e32 v104, 16, v129
	v_pk_mul_f32 v[192:193], v[192:193], v[210:211]
	v_and_b32_e32 v105, 0xffff0000, v129
	v_cvt_pk_bf16_f32 v187, v192, v193
	v_pk_fma_f32 v[188:189], v[62:63], v[104:105], v[188:189]
	ds_write2st64_b32 v95, v56, v187 offset1:68
	v_mul_f32_e32 v187, 0xbfb8aa3b, v188
	v_exp_f32_e32 v187, v187
	v_mov_b32_e32 v56, v190
	v_mov_b32_e32 v57, v192
	v_mov_b32_e32 v192, v191
	v_add_f32_e32 v187, 1.0, v187
	v_pk_mul_f32 v[56:57], v[56:57], v[52:53]
	v_pk_mul_f32 v[52:53], v[192:193], v[52:53]
	v_rcp_f32_e32 v192, v187
	v_mul_f32_e32 v187, 0xbfb8aa3b, v189
	v_exp_f32_e32 v187, v187
	v_pk_fma_f32 v[106:107], v[68:69], v[110:111], v[106:107]
	v_pk_fma_f32 v[108:109], v[66:67], v[78:79], v[108:109]
	v_pk_fma_f32 v[190:191], v[72:73], v[80:81], v[106:107]
	v_lshlrev_b32_e32 v106, 16, v131
	v_and_b32_e32 v107, 0xffff0000, v131
	v_pk_fma_f32 v[190:191], v[64:65], v[106:107], v[190:191]
	v_add_f32_e32 v187, 1.0, v187
	v_rcp_f32_e32 v193, v187
	v_mul_f32_e32 v187, 0xbfb8aa3b, v190
	v_exp_f32_e32 v187, v187
	v_pk_fma_f32 v[108:109], v[70:71], v[104:105], v[108:109]
	v_pk_mul_f32 v[188:189], v[188:189], v[192:193]
	v_sub_f32_e32 v42, v184, v42
	v_add_f32_e32 v187, 1.0, v187
	v_rcp_f32_e32 v192, v187
	v_mul_f32_e32 v187, 0xbfb8aa3b, v191
	v_exp_f32_e32 v187, v187
	v_pk_mul_f32 v[188:189], v[188:189], s[80:81] op_sel_hi:[1,0]
	s_waitcnt lgkmcnt(3)
	v_add_f32_e32 v42, v42, v46
	v_pk_fma_f32 v[110:111], v[60:61], v[110:111], v[76:77]
	v_add_f32_e32 v187, 1.0, v187
	v_rcp_f32_e32 v193, v187
	v_cvt_pk_bf16_f32 v187, v188, v189
	v_and_b32_e32 v189, 0xffff0000, v132
	v_pk_fma_f32 v[110:111], v[68:69], v[80:81], v[110:111]
	v_pk_mul_f32 v[190:191], v[190:191], v[192:193]
	v_pk_fma_f32 v[110:111], v[72:73], v[106:107], v[110:111]
	v_cvt_pk_bf16_f32 v188, v190, v191
	ds_write2st64_b32 v159, v187, v188 offset1:68
	v_lshlrev_b32_e32 v188, 16, v132
	v_pk_fma_f32 v[108:109], v[62:63], v[188:189], v[108:109]
	v_lshlrev_b32_e32 v192, 16, v133
	v_mul_f32_e32 v46, 0xbfb8aa3b, v108
	v_exp_f32_e32 v46, v46
	v_and_b32_e32 v193, 0xffff0000, v133
	v_pk_fma_f32 v[110:111], v[64:65], v[192:193], v[110:111]
	v_pk_fma_f32 v[78:79], v[58:59], v[78:79], v[74:75]
	v_add_f32_e32 v46, 1.0, v46
	v_rcp_f32_e32 v210, v46
	v_mul_f32_e32 v46, 0xbfb8aa3b, v109
	v_exp_f32_e32 v46, v46
	v_pk_fma_f32 v[58:59], v[58:59], v[104:105], v[74:75]
	v_pk_fma_f32 v[78:79], v[66:67], v[104:105], v[78:79]
	v_pk_fma_f32 v[58:59], v[66:67], v[188:189], v[58:59]
	v_add_f32_e32 v46, 1.0, v46
	v_rcp_f32_e32 v211, v46
	v_mul_f32_e32 v46, 0xbfb8aa3b, v110
	v_exp_f32_e32 v46, v46
	v_pk_fma_f32 v[78:79], v[70:71], v[188:189], v[78:79]
	v_pk_mul_f32 v[108:109], v[108:109], v[210:211]
	v_lshlrev_b32_e32 v66, 16, v136
	v_add_f32_e32 v46, 1.0, v46
	v_rcp_f32_e32 v210, v46
	v_mul_f32_e32 v46, 0xbfb8aa3b, v111
	v_exp_f32_e32 v46, v46
	v_pk_mul_f32 v[108:109], v[108:109], s[80:81] op_sel_hi:[1,0]
	v_and_b32_e32 v67, 0xffff0000, v136
	v_sub_f32_e32 v44, v184, v44
	v_add_f32_e32 v46, 1.0, v46
; #define LAS __attribute__((address_space(3)))
; __device__ __forceinline__ unsigned pk2(float lo, float hi) { const f32x2 v = {lo, hi}; const bf16x2n b = __builtin_convertvector(v, bf16x2n); return __builtin_bit_cast(unsigned, b); }
; __device__ __forceinline__ void ml_block(KP p, int e, int b, int hd, int half, LAS unsigned char* lds, const bf16_t* P, bf16_t* YB) {
;     ...
;                 const float wkj = __expf(blast - Bc[j] + Ip[j]);
;                 kw0[i] = wkj * k0; kw1[i] = wkj * k1;
;             }
;             { u32x4 w; w.x = pk2(kw0[0], kw0[1]); w.y = pk2(kw0[2], kw0[3]); w.z = pk2(kw0[4], kw0[5]); w.w = pk2(kw0[6], kw0[7]); *(LAS u32x4*)(KwT + (2 * d2) * 72 + tg * 8) = w; }
;             { u32x4 w; w.x = pk2(kw1[0], kw1[1]); w.y = pk2(kw1[2], kw1[3]); w.z = pk2(kw1[4], kw1[5]); w.w = pk2(kw1[6], kw1[7]); *(LAS u32x4*)(KwT + (2 * d2 + 1) * 72 + tg * 8) = w; }
;             { u32x4 w; w.x = (vr[0] & 0xFFFFu) | (vr[1] << 16); w.y = (vr[2] & 0xFFFFu) | (vr[3] << 16); w.z = (vr[4] & 0xFFFFu) | (vr[5] << 16); w.w = (vr[6] & 0xFFFFu) | (vr[7] << 16); *(LAS u32x4*)(VT + (2 * d2) * 72 + tg * 8) = w; }
;             { u32x4 w; w.x = (vr[0] >> 16) | (vr[1] & 0xFFFF0000u); w.y = (vr[2] >> 16) | (vr[3] & 0xFFFF0000u); w.z = (vr[4] >> 16) | (vr[5] & 0xFFFF0000u); w.w = (vr[6] >> 16) | (vr[7] & 0xFFFF0000u); *(LAS u32x4*)(VT + (2 * d2 + 1) * 72 + tg * 8) = w; }
;         }
;         if (has_next) load_qkv(tb + 64);
	v_rcp_f32_e32 v211, v46
	v_cvt_pk_bf16_f32 v46, v108, v109
	v_and_b32_e32 v109, 0xffff0000, v134
	v_add_f32_e32 v44, v44, v48
	v_pk_mul_f32 v[110:111], v[110:111], v[210:211]
	v_sub_f32_e32 v43, v184, v43
	v_cvt_pk_bf16_f32 v108, v110, v111
	ds_write2st64_b32 v160, v46, v108 offset1:68
	v_lshlrev_b32_e32 v108, 16, v134
	v_pk_fma_f32 v[58:59], v[70:71], v[108:109], v[58:59]
	v_pk_fma_f32 v[78:79], v[62:63], v[108:109], v[78:79]
	v_pk_fma_f32 v[58:59], v[62:63], v[66:67], v[58:59]
	v_mul_f32_e32 v187, 0xbfb8aa3b, v78
	v_mul_f32_e32 v48, 0xbfb8aa3b, v58
	v_exp_f32_e32 v187, v187
	v_exp_f32_e32 v48, v48
	v_add_f32_e32 v43, v43, v47
	v_mul_f32_e32 v42, 0x3fb8aa3b, v42
	v_mul_f32_e32 v43, 0x3fb8aa3b, v43
	v_exp_f32_e32 v42, v42
	v_exp_f32_e32 v43, v43
	v_add_f32_e32 v187, 1.0, v187
	v_add_f32_e32 v48, 1.0, v48
	v_mov_b32_e32 v46, v190
	v_rcp_f32_e32 v190, v187
	v_mul_f32_e32 v187, 0xbfb8aa3b, v79
	v_rcp_f32_e32 v62, v48
	v_mul_f32_e32 v48, 0xbfb8aa3b, v59
	v_exp_f32_e32 v187, v187
	v_exp_f32_e32 v48, v48
	v_mov_b32_e32 v47, v110
	v_mov_b32_e32 v110, v191
	v_pk_fma_f32 v[80:81], v[60:61], v[80:81], v[76:77]
	v_pk_fma_f32 v[60:61], v[60:61], v[106:107], v[76:77]
	v_pk_mul_f32 v[46:47], v[46:47], v[42:43]
	v_pk_mul_f32 v[42:43], v[110:111], v[42:43]
	v_pk_fma_f32 v[80:81], v[68:69], v[106:107], v[80:81]
	v_lshlrev_b32_e32 v110, 16, v135
	v_and_b32_e32 v111, 0xffff0000, v135
	v_pk_fma_f32 v[60:61], v[68:69], v[192:193], v[60:61]
	v_pk_fma_f32 v[80:81], v[72:73], v[192:193], v[80:81]
	v_pk_fma_f32 v[60:61], v[72:73], v[110:111], v[60:61]
	v_lshlrev_b32_e32 v68, 16, v137
	v_and_b32_e32 v69, 0xffff0000, v137
	v_pk_fma_f32 v[80:81], v[64:65], v[110:111], v[80:81]
	v_add_f32_e32 v187, 1.0, v187
	v_pk_fma_f32 v[60:61], v[64:65], v[68:69], v[60:61]
	v_add_f32_e32 v48, 1.0, v48
	v_rcp_f32_e32 v191, v187
	v_mul_f32_e32 v187, 0xbfb8aa3b, v80
	v_rcp_f32_e32 v63, v48
	v_mul_f32_e32 v48, 0xbfb8aa3b, v60
	v_exp_f32_e32 v187, v187
	v_exp_f32_e32 v48, v48
	v_pk_mul_f32 v[78:79], v[78:79], v[190:191]
	v_pk_mul_f32 v[58:59], v[58:59], v[62:63]
	v_add_f32_e32 v187, 1.0, v187
	v_add_f32_e32 v48, 1.0, v48
	v_rcp_f32_e32 v190, v187
	v_mul_f32_e32 v187, 0xbfb8aa3b, v81
	v_rcp_f32_e32 v62, v48
	v_mul_f32_e32 v48, 0xbfb8aa3b, v61
	v_exp_f32_e32 v187, v187
	v_exp_f32_e32 v48, v48
	v_sub_f32_e32 v45, v184, v45
	v_add_f32_e32 v45, v45, v49
	v_add_f32_e32 v187, 1.0, v187
	v_add_f32_e32 v48, 1.0, v48
	v_rcp_f32_e32 v191, v187
	v_rcp_f32_e32 v63, v48
	v_mul_f32_e32 v44, 0x3fb8aa3b, v44
	v_mul_f32_e32 v45, 0x3fb8aa3b, v45
	v_exp_f32_e32 v44, v44
	v_exp_f32_e32 v45, v45
	v_pk_mul_f32 v[78:79], v[78:79], s[80:81] op_sel_hi:[1,0]
	v_pk_mul_f32 v[80:81], v[80:81], v[190:191]
	v_pk_mul_f32 v[58:59], v[58:59], s[80:81] op_sel_hi:[1,0]
	v_pk_mul_f32 v[60:61], v[60:61], v[62:63]
	v_cvt_pk_bf16_f32 v78, v78, v79
	v_cvt_pk_bf16_f32 v79, v80, v81
	v_cvt_pk_bf16_f32 v48, v58, v59
	v_cvt_pk_bf16_f32 v58, v60, v61
	ds_write2st64_b32 v161, v78, v79 offset1:68
	ds_write2st64_b32 v162, v48, v58 offset1:68
	v_mov_b32_e32 v48, v80
	v_mov_b32_e32 v49, v60
	v_pk_mul_f32 v[48:49], v[48:49], v[44:45]
	v_mov_b32_e32 v60, v81
	v_pk_mul_f32 v[58:59], v[60:61], v[44:45]
	v_cvt_pk_bf16_f32 v44, v54, v55
	v_cvt_pk_bf16_f32 v45, v56, v57
	v_cvt_pk_bf16_f32 v46, v46, v47
	v_cvt_pk_bf16_f32 v47, v48, v49
	ds_write_b128 v85, v[44:47] offset:44032
	v_cvt_pk_bf16_f32 v44, v50, v51
	v_cvt_pk_bf16_f32 v45, v52, v53
	v_cvt_pk_bf16_f32 v46, v42, v43
	v_cvt_pk_bf16_f32 v47, v58, v59
	ds_write_b128 v85, v[44:47] offset:44176
	s_waitcnt vmcnt(7)
	v_and_b32_e32 v42, 0xffff, v178
	s_waitcnt vmcnt(5)
	v_and_b32_e32 v43, 0xffff, v180
	s_waitcnt vmcnt(3)
	v_and_b32_e32 v44, 0xffff, v182
	s_waitcnt vmcnt(1)
	v_and_b32_e32 v45, 0xffff, v185
	v_lshl_or_b32 v42, v179, 16, v42
	v_lshl_or_b32 v43, v181, 16, v43
	v_lshl_or_b32 v44, v183, 16, v44
	s_waitcnt vmcnt(0)
	v_lshl_or_b32 v45, v186, 16, v45
	ds_write_b128 v85, v[42:45] offset:62464
	v_lshrrev_b32_e32 v42, 16, v178
	v_lshrrev_b32_e32 v43, 16, v180
	v_lshrrev_b32_e32 v44, 16, v182
	v_lshrrev_b32_e32 v45, 16, v185
	s_cmpk_eq_i32 s52, 0xfc0
	v_and_or_b32 v42, v179, s5, v42
	v_and_or_b32 v43, v181, s5, v43
	v_and_or_b32 v44, v183, s5, v44
	v_and_or_b32 v45, v186, s5, v45
	ds_write_b128 v85, v[42:45] offset:62608
	s_cbranch_scc1 .LBB0_351
	v_add_u32_e32 v44, s52, v167
	v_add_u32_e32 v45, 0xffff003d, v44
	v_mad_u64_u32 v[46:47], s[78:79], v45, s81, v[96:97]
	s_nop 4
	s_mov_b64 s[78:79], 0x1a00
	global_load_dword v113, v[46:47], off offset:2048
	global_load_dword v115, v[46:47], off offset:3072
	v_lshl_add_u64 v[42:43], v[46:47], 0, s[78:79]
	global_load_dword v116, v[42:43], off offset:2048
	global_load_dword v117, v[42:43], off offset:3072
	v_lshl_add_u64 v[46:47], v[42:43], 0, s[78:79]
	global_load_dword v118, v[46:47], off offset:2048
	global_load_dword v119, v[46:47], off offset:3072
	v_lshl_add_u64 v[42:43], v[46:47], 0, s[78:79]
	global_load_dword v120, v[42:43], off offset:2048
	global_load_dword v121, v[42:43], off offset:3072
	v_lshl_add_u64 v[46:47], v[42:43], 0, s[78:79]
	global_load_dword v122, v[46:47], off offset:2048
	global_load_dword v123, v[46:47], off offset:3072
	v_lshl_add_u64 v[42:43], v[46:47], 0, s[78:79]
	global_load_dword v125, v[42:43], off offset:2048
	global_load_dword v126, v[42:43], off offset:3072
	v_lshl_add_u64 v[46:47], v[42:43], 0, s[78:79]
	global_load_dword v127, v[46:47], off offset:2048
	global_load_dword v128, v[46:47], off offset:3072
	v_lshl_add_u64 v[42:43], v[46:47], 0, s[78:79]
	global_load_dword v129, v[42:43], off offset:2048
	global_load_dword v131, v[42:43], off offset:3072
	v_lshl_add_u64 v[46:47], v[42:43], 0, s[78:79]
	global_load_dword v132, v[46:47], off offset:2048
	global_load_dword v133, v[46:47], off offset:3072
	v_lshl_add_u64 v[42:43], v[46:47], 0, s[78:79]
	global_load_dword v134, v[42:43], off offset:2048
	global_load_dword v135, v[42:43], off offset:3072
	v_lshl_add_u64 v[46:47], v[42:43], 0, s[78:79]
	global_load_dword v136, v[46:47], off offset:2048
	global_load_dword v137, v[46:47], off offset:3072
